# group-barrier poll loops back off longer between polls (s_sleep 10 instead of 1): fewer reads of the barrier counter line while the others arrive
# speedup vs baseline: 1.0040x; 1.0040x over previous
; __device__ __forceinline__ unsigned xb_ld(unsigned* p)              { return __hip_atomic_load(p, __ATOMIC_RELAXED, __HIP_MEMORY_SCOPE_AGENT); }
; __device__ __forceinline__ void grp_barrier(unsigned* cntw, unsigned* tmo) {
;     ...
;         while (xb_ld(cntw) < target) { __builtin_amdgcn_s_sleep(1);
;             if ((++sp & 255u) == 0u) { if (xb_ld(tmo)) break; if (sp > XB_SPIN_CAP) { atomicAdd(tmo, 1u); break; } } }
.LBB0_461:
	s_and_b32 s28, s11, 0xff
	s_mov_b64 s[26:27], -1
	s_cmp_lg_u32 s28, 0
	s_mov_b64 s[40:41], -1
	s_sleep 10
	s_cbranch_scc0 .LBB0_464
	s_and_b64 vcc, exec, s[40:41]
	s_cbranch_vccz .LBB0_460

; __device__ __forceinline__ unsigned xb_ld(unsigned* p)              { return __hip_atomic_load(p, __ATOMIC_RELAXED, __HIP_MEMORY_SCOPE_AGENT); }
; __device__ __forceinline__ void grp_barrier(unsigned* cntw, unsigned* tmo) {
;     ...
;         while (xb_ld(cntw) < target) { __builtin_amdgcn_s_sleep(1);
;             if ((++sp & 255u) == 0u) { if (xb_ld(tmo)) break; if (sp > XB_SPIN_CAP) { atomicAdd(tmo, 1u); break; } } }
.LBB0_667:
	s_and_b32 s14, s11, 0xff
	s_mov_b64 s[20:21], -1
	s_cmp_lg_u32 s14, 0
	s_mov_b64 s[26:27], -1
	s_sleep 10
	s_cbranch_scc0 .LBB0_670
	s_and_b64 vcc, exec, s[26:27]
	s_cbranch_vccz .LBB0_666

; __device__ __forceinline__ unsigned xb_ld(unsigned* p)              { return __hip_atomic_load(p, __ATOMIC_RELAXED, __HIP_MEMORY_SCOPE_AGENT); }
; __device__ __forceinline__ void grp_barrier(unsigned* cntw, unsigned* tmo) {
;     ...
;         while (xb_ld(cntw) < target) { __builtin_amdgcn_s_sleep(1);
;             if ((++sp & 255u) == 0u) { if (xb_ld(tmo)) break; if (sp > XB_SPIN_CAP) { atomicAdd(tmo, 1u); break; } } }
.LBB0_902:
	s_and_b32 s24, s28, 0xff
	s_mov_b64 s[20:21], -1
	s_cmp_lg_u32 s24, 0
	s_mov_b64 s[26:27], -1
	s_sleep 10
	s_cbranch_scc0 .LBB0_905
	s_and_b64 vcc, exec, s[26:27]
	s_cbranch_vccz .LBB0_901
